# grid barrier: non-leader workgroups poll the cross-XCC release generation directly instead of the relayed per-XCC one
# speedup vs baseline: 1.0110x; 1.0110x over previous
.LBB0_50:
	s_lshl_b32 s2, s2, 6
	s_add_i32 s6, s2, 0x500
	s_mov_b32 s7, 0
	s_lshl_b64 s[4:5], s[6:7], 2
	s_add_u32 s4, s36, s4
	s_addc_u32 s5, s37, s5
	v_mov_b32_e32 v1, 1
	v_mov_b64_e32 v[4:5], s[4:5]
	flat_atomic_add v1, v[4:5], v1 sc0
	v_cvt_f32_u32_e32 v3, v2
	v_sub_u32_e32 v4, 0, v2
	v_rcp_iflag_f32_e32 v3, v3
	s_nop 0
	v_mul_f32_e32 v3, 0x4f7ffffe, v3
	v_cvt_u32_f32_e32 v3, v3
	v_mul_lo_u32 v4, v4, v3
	v_mul_hi_u32 v4, v3, v4
	v_add_u32_e32 v3, v3, v4
	s_waitcnt vmcnt(0) lgkmcnt(0)
	v_mul_hi_u32 v3, v1, v3
	v_mul_lo_u32 v5, v3, v2
	v_add_u32_e32 v4, 1, v1
	v_sub_u32_e32 v1, v1, v5
	v_add_u32_e32 v6, 1, v3
	v_cmp_ge_u32_e32 vcc, v1, v2
	v_sub_u32_e32 v5, v1, v2
	s_nop 0
	v_cndmask_b32_e32 v3, v3, v6, vcc
	v_cndmask_b32_e32 v1, v1, v5, vcc
	v_add_u32_e32 v5, 1, v3
	v_cmp_ge_u32_e32 vcc, v1, v2
	s_nop 1
	v_cndmask_b32_e32 v1, v3, v5, vcc
	v_mad_u64_u32 v[2:3], s[4:5], v2, v1, v[2:3]
	v_cmp_ne_u32_e32 vcc, v4, v2
	s_and_saveexec_b64 s[4:5], vcc
	s_xor_b64 s[4:5], exec, s[4:5]
	s_cbranch_execz .LBB0_63
	s_add_i32 s6, s2, 0x900
	s_lshl_b64 s[6:7], s[6:7], 2
	s_add_u32 s8, s36, s6
	s_addc_u32 s9, s37, s7
	s_add_u32 s8, s36, 0x3500
	s_addc_u32 s9, s37, 0
	v_mov_b64_e32 v[2:3], s[8:9]
	flat_load_dword v0, v[2:3] sc1
	s_waitcnt vmcnt(0) lgkmcnt(0)
	v_cmp_eq_u32_e32 vcc, v0, v1
	s_and_saveexec_b64 s[6:7], vcc
	s_cbranch_execz .LBB0_62
	s_mov_b32 s24, 1
	s_mov_b64 s[10:11], 0
	s_branch .LBB0_54

.LBB0_192:
	s_lshl_b32 s3, s3, 6
	s_add_i32 s0, s3, 0x500
	s_lshl_b64 s[4:5], s[0:1], 2
	s_add_u32 s4, s40, s4
	s_addc_u32 s5, s41, s5
	v_mov_b64_e32 v[4:5], s[4:5]
	flat_atomic_add v3, v[4:5], v214 sc0
	v_cvt_f32_u32_e32 v1, v2
	v_sub_u32_e32 v4, 0, v2
	v_rcp_iflag_f32_e32 v1, v1
	s_nop 0
	v_mul_f32_e32 v1, 0x4f7ffffe, v1
	v_cvt_u32_f32_e32 v1, v1
	v_mul_lo_u32 v4, v4, v1
	v_mul_hi_u32 v4, v1, v4
	v_add_u32_e32 v1, v1, v4
	s_waitcnt vmcnt(0) lgkmcnt(0)
	v_mul_hi_u32 v1, v3, v1
	v_mul_lo_u32 v4, v1, v2
	v_sub_u32_e32 v4, v3, v4
	v_cmp_ge_u32_e32 vcc, v4, v2
	v_add_u32_e32 v5, 1, v1
	s_nop 0
	v_cndmask_b32_e32 v1, v1, v5, vcc
	v_sub_u32_e32 v5, v4, v2
	v_cndmask_b32_e32 v4, v4, v5, vcc
	v_cmp_ge_u32_e32 vcc, v4, v2
	v_add_u32_e32 v4, 1, v1
	s_nop 0
	v_cndmask_b32_e32 v1, v1, v4, vcc
	v_add_u32_e32 v4, 1, v3
	v_mad_u64_u32 v[2:3], s[4:5], v2, v1, v[2:3]
	v_cmp_ne_u32_e32 vcc, v4, v2
	s_and_saveexec_b64 s[4:5], vcc
	s_xor_b64 s[6:7], exec, s[4:5]
	s_cbranch_execz .LBB0_205
	s_add_i32 s0, s3, 0x900
	s_lshl_b64 s[4:5], s[0:1], 2
	s_add_u32 s10, s40, s4
	s_addc_u32 s11, s41, s5
	s_add_u32 s10, s40, 0x3500
	s_addc_u32 s11, s41, 0
	v_mov_b64_e32 v[2:3], s[10:11]
	flat_load_dword v0, v[2:3] sc1
	s_waitcnt vmcnt(0) lgkmcnt(0)
	v_cmp_eq_u32_e32 vcc, v0, v1
	s_and_saveexec_b64 s[8:9], vcc
	s_cbranch_execz .LBB0_204
	s_mov_b32 s4, 1
	s_mov_b64 s[12:13], 0
	s_branch .LBB0_196

.LBB0_370:
	s_lshl_b32 s3, s3, 6
	s_add_i32 s0, s3, 0x500
	s_lshl_b64 s[4:5], s[0:1], 2
	s_add_u32 s4, s42, s4
	s_addc_u32 s5, s43, s5
	v_mov_b64_e32 v[4:5], s[4:5]
	flat_atomic_add v3, v[4:5], v214 sc0
	v_cvt_f32_u32_e32 v1, v2
	v_sub_u32_e32 v4, 0, v2
	v_rcp_iflag_f32_e32 v1, v1
	s_nop 0
	v_mul_f32_e32 v1, 0x4f7ffffe, v1
	v_cvt_u32_f32_e32 v1, v1
	v_mul_lo_u32 v4, v4, v1
	v_mul_hi_u32 v4, v1, v4
	v_add_u32_e32 v1, v1, v4
	s_waitcnt vmcnt(0) lgkmcnt(0)
	v_mul_hi_u32 v1, v3, v1
	v_mul_lo_u32 v4, v1, v2
	v_sub_u32_e32 v4, v3, v4
	v_cmp_ge_u32_e32 vcc, v4, v2
	v_add_u32_e32 v5, 1, v1
	s_nop 0
	v_cndmask_b32_e32 v1, v1, v5, vcc
	v_sub_u32_e32 v5, v4, v2
	v_cndmask_b32_e32 v4, v4, v5, vcc
	v_cmp_ge_u32_e32 vcc, v4, v2
	v_add_u32_e32 v4, 1, v1
	s_nop 0
	v_cndmask_b32_e32 v1, v1, v4, vcc
	v_add_u32_e32 v4, 1, v3
	v_mad_u64_u32 v[2:3], s[4:5], v2, v1, v[2:3]
	v_cmp_ne_u32_e32 vcc, v4, v2
	s_and_saveexec_b64 s[4:5], vcc
	s_xor_b64 s[8:9], exec, s[4:5]
	s_cbranch_execz .LBB0_383
	s_add_i32 s0, s3, 0x900
	s_lshl_b64 s[4:5], s[0:1], 2
	s_add_u32 s12, s42, s4
	s_addc_u32 s13, s43, s5
	s_add_u32 s12, s42, 0x3500
	s_addc_u32 s13, s43, 0
	v_mov_b64_e32 v[2:3], s[12:13]
	flat_load_dword v0, v[2:3] sc1
	s_waitcnt vmcnt(0) lgkmcnt(0)
	v_cmp_eq_u32_e32 vcc, v0, v1
	s_and_saveexec_b64 s[10:11], vcc
	s_cbranch_execz .LBB0_382
	s_mov_b32 s4, 1
	s_mov_b64 s[14:15], 0
	s_branch .LBB0_374

.LBB0_1093:
	s_lshl_b32 s3, s3, 6
	s_add_i32 s0, s3, 0x500
	s_lshl_b64 s[4:5], s[0:1], 2
	s_add_u32 s4, s38, s4
	s_addc_u32 s5, s39, s5
	v_mov_b64_e32 v[4:5], s[4:5]
	flat_atomic_add v3, v[4:5], v214 sc0
	v_cvt_f32_u32_e32 v1, v2
	v_sub_u32_e32 v4, 0, v2
	v_rcp_iflag_f32_e32 v1, v1
	s_nop 0
	v_mul_f32_e32 v1, 0x4f7ffffe, v1
	v_cvt_u32_f32_e32 v1, v1
	v_mul_lo_u32 v4, v4, v1
	v_mul_hi_u32 v4, v1, v4
	v_add_u32_e32 v1, v1, v4
	s_waitcnt vmcnt(0) lgkmcnt(0)
	v_mul_hi_u32 v1, v3, v1
	v_mul_lo_u32 v4, v1, v2
	v_sub_u32_e32 v4, v3, v4
	v_cmp_ge_u32_e32 vcc, v4, v2
	v_add_u32_e32 v5, 1, v1
	s_nop 0
	v_cndmask_b32_e32 v1, v1, v5, vcc
	v_sub_u32_e32 v5, v4, v2
	v_cndmask_b32_e32 v4, v4, v5, vcc
	v_cmp_ge_u32_e32 vcc, v4, v2
	v_add_u32_e32 v4, 1, v1
	s_nop 0
	v_cndmask_b32_e32 v1, v1, v4, vcc
	v_add_u32_e32 v4, 1, v3
	v_mad_u64_u32 v[2:3], s[4:5], v2, v1, v[2:3]
	v_cmp_ne_u32_e32 vcc, v4, v2
	s_and_saveexec_b64 s[4:5], vcc
	s_xor_b64 s[4:5], exec, s[4:5]
	s_cbranch_execz .LBB0_1106
	s_add_i32 s0, s3, 0x900
	s_lshl_b64 s[6:7], s[0:1], 2
	s_add_u32 s8, s38, s6
	s_addc_u32 s9, s39, s7
	s_add_u32 s8, s38, 0x3500
	s_addc_u32 s9, s39, 0
	v_mov_b64_e32 v[2:3], s[8:9]
	flat_load_dword v0, v[2:3] sc1
	s_waitcnt vmcnt(0) lgkmcnt(0)
	v_cmp_eq_u32_e32 vcc, v0, v1
	s_and_saveexec_b64 s[6:7], vcc
	s_cbranch_execz .LBB0_1105
	s_mov_b32 s24, 1
	s_mov_b64 s[10:11], 0
	s_branch .LBB0_1097
